# GLA+retention: reduce-scatter (5 masked DPP adds + 1 DPP mov) instead of 8-op all-reduce, LDS reads as wait-state fillers
# speedup vs baseline: 1.1793x; 1.0060x over previous
.Lret2_loop:
	global_load_dword v84, v32, s[10:11]
	global_load_dword v85, v32, s[10:11] offset:-1024
	global_load_dword v86, v33, s[10:11]
	global_load_dword v87, v33, s[10:11] offset:-1024
	global_load_dword v88, v34, s[10:11]
	global_load_dword v90, v35, s[12:13]
	global_load_dword v91, v35, s[12:13] offset:4
	s_add_u32 s10, s10, 0x18000
	s_addc_u32 s11, s11, 0
	s_add_u32 s12, s12, 0x4000
	s_addc_u32 s13, s13, 0
	s_waitcnt lgkmcnt(0)
	v_pk_mul_f32 v[40:41], v[40:41], v[42:43]
	v_rcp_f32_e32 v40, v41
	s_nop 0
	v_pk_mul_f32 v[44:45], v[64:65], v[40:41] op_sel_hi:[1,0]
	v_pk_fma_f32 v[6:7], v[44:45], v[48:49], v[6:7] op_sel_hi:[1,0,1]
	v_pk_mul_f32 v[38:39], v[6:7], v[48:49] op_sel:[0,1] op_sel_hi:[1,1]
	v_pk_fma_f32 v[8:9], v[44:45], v[50:51], v[8:9] op_sel_hi:[1,0,1]
	v_pk_fma_f32 v[38:39], v[8:9], v[50:51], v[38:39] op_sel:[0,1,0] op_sel_hi:[1,1,1]
	v_pk_fma_f32 v[10:11], v[44:45], v[52:53], v[10:11] op_sel_hi:[1,0,1]
	v_pk_fma_f32 v[38:39], v[10:11], v[52:53], v[38:39] op_sel:[0,1,0] op_sel_hi:[1,1,1]
	v_pk_fma_f32 v[12:13], v[44:45], v[54:55], v[12:13] op_sel_hi:[1,0,1]
	v_pk_fma_f32 v[38:39], v[12:13], v[54:55], v[38:39] op_sel:[0,1,0] op_sel_hi:[1,1,1]
	v_pk_fma_f32 v[14:15], v[44:45], v[56:57], v[14:15] op_sel_hi:[1,0,1]
	v_pk_fma_f32 v[38:39], v[14:15], v[56:57], v[38:39] op_sel:[0,1,0] op_sel_hi:[1,1,1]
	v_pk_fma_f32 v[16:17], v[44:45], v[58:59], v[16:17] op_sel_hi:[1,0,1]
	v_pk_fma_f32 v[38:39], v[16:17], v[58:59], v[38:39] op_sel:[0,1,0] op_sel_hi:[1,1,1]
	v_pk_fma_f32 v[18:19], v[44:45], v[60:61], v[18:19] op_sel_hi:[1,0,1]
	v_pk_fma_f32 v[38:39], v[18:19], v[60:61], v[38:39] op_sel:[0,1,0] op_sel_hi:[1,1,1]
	v_pk_fma_f32 v[20:21], v[44:45], v[62:63], v[20:21] op_sel_hi:[1,0,1]
	v_pk_fma_f32 v[38:39], v[20:21], v[62:63], v[38:39] op_sel:[0,1,0] op_sel_hi:[1,1,1]
	s_add_u32 s14, s14, 0x1000
	s_addc_u32 s15, s15, 0
	v_add_f32_dpp v38, v38, v38 row_ror:8 row_mask:0xf bank_mask:0x3 bound_ctrl:1
	v_add_f32_dpp v38, v39, v39 row_ror:8 row_mask:0xf bank_mask:0xc bound_ctrl:1
	ds_read_b128 v[66:69], v22 offset:9216
	ds_read_b128 v[70:73], v22 offset:9472
	v_add_f32_dpp v38, v38, v38 row_half_mirror row_mask:0xf bank_mask:0xf bound_ctrl:1
	ds_read_b128 v[74:77], v22 offset:9728
	ds_read_b128 v[78:81], v22 offset:9984
	v_add_f32_dpp v38, v38, v38 quad_perm:[1,0,3,2] row_mask:0xf bank_mask:0xf bound_ctrl:1
	ds_read_b64 v[82:83], v23 offset:20736
	s_nop 0
	v_add_f32_dpp v38, v38, v38 quad_perm:[2,3,0,1] row_mask:0xf bank_mask:0xf bound_ctrl:1
	s_nop 1
	v_mov_b32_dpp v39, v38 row_ror:8 row_mask:0xf bank_mask:0xf bound_ctrl:1
	v_pk_mul_f32 v[38:39], v[38:39], v[40:41] op_sel:[0,1] op_sel_hi:[1,1]
	v_cvt_pk_bf16_f32 v47, v38, v39
	s_mov_b64 exec, s[2:3]
	global_store_dword v46, v47, s[14:15] offset:-4096
	s_mov_b64 exec, -1
	s_waitcnt lgkmcnt(0)
	v_pk_mul_f32 v[40:41], v[40:41], v[42:43]
	v_pk_mul_f32 v[44:45], v[82:83], v[40:41] op_sel_hi:[1,0]
	v_pk_fma_f32 v[6:7], v[44:45], v[66:67], v[6:7] op_sel_hi:[1,0,1]
	v_pk_mul_f32 v[38:39], v[6:7], v[66:67] op_sel:[0,1] op_sel_hi:[1,1]
	v_pk_fma_f32 v[8:9], v[44:45], v[68:69], v[8:9] op_sel_hi:[1,0,1]
	v_pk_fma_f32 v[38:39], v[8:9], v[68:69], v[38:39] op_sel:[0,1,0] op_sel_hi:[1,1,1]
	v_pk_fma_f32 v[10:11], v[44:45], v[70:71], v[10:11] op_sel_hi:[1,0,1]
	v_pk_fma_f32 v[38:39], v[10:11], v[70:71], v[38:39] op_sel:[0,1,0] op_sel_hi:[1,1,1]
	v_pk_fma_f32 v[12:13], v[44:45], v[72:73], v[12:13] op_sel_hi:[1,0,1]
	v_pk_fma_f32 v[38:39], v[12:13], v[72:73], v[38:39] op_sel:[0,1,0] op_sel_hi:[1,1,1]
	v_pk_fma_f32 v[14:15], v[44:45], v[74:75], v[14:15] op_sel_hi:[1,0,1]
	v_pk_fma_f32 v[38:39], v[14:15], v[74:75], v[38:39] op_sel:[0,1,0] op_sel_hi:[1,1,1]
	v_pk_fma_f32 v[16:17], v[44:45], v[76:77], v[16:17] op_sel_hi:[1,0,1]
	v_pk_fma_f32 v[38:39], v[16:17], v[76:77], v[38:39] op_sel:[0,1,0] op_sel_hi:[1,1,1]
	v_pk_fma_f32 v[18:19], v[44:45], v[78:79], v[18:19] op_sel_hi:[1,0,1]
	v_pk_fma_f32 v[38:39], v[18:19], v[78:79], v[38:39] op_sel:[0,1,0] op_sel_hi:[1,1,1]
	v_pk_fma_f32 v[20:21], v[44:45], v[80:81], v[20:21] op_sel_hi:[1,0,1]
	v_pk_fma_f32 v[38:39], v[20:21], v[80:81], v[38:39] op_sel:[0,1,0] op_sel_hi:[1,1,1]
	s_add_u32 s14, s14, 0x1000
	s_addc_u32 s15, s15, 0
	v_add_f32_dpp v38, v38, v38 row_ror:8 row_mask:0xf bank_mask:0x3 bound_ctrl:1
	v_add_f32_dpp v38, v39, v39 row_ror:8 row_mask:0xf bank_mask:0xc bound_ctrl:1
	ds_read_b128 v[48:51], v22 offset:10240
	ds_read_b128 v[52:55], v22 offset:10496
	v_add_f32_dpp v38, v38, v38 row_half_mirror row_mask:0xf bank_mask:0xf bound_ctrl:1
	ds_read_b128 v[56:59], v22 offset:10752
	ds_read_b128 v[60:63], v22 offset:11008
	v_add_f32_dpp v38, v38, v38 quad_perm:[1,0,3,2] row_mask:0xf bank_mask:0xf bound_ctrl:1
	ds_read_b64 v[64:65], v23 offset:20992
	s_nop 0
	v_add_f32_dpp v38, v38, v38 quad_perm:[2,3,0,1] row_mask:0xf bank_mask:0xf bound_ctrl:1
	s_nop 1
	v_mov_b32_dpp v39, v38 row_ror:8 row_mask:0xf bank_mask:0xf bound_ctrl:1
	v_pk_mul_f32 v[38:39], v[38:39], v[40:41] op_sel:[0,1] op_sel_hi:[1,1]
	v_cvt_pk_bf16_f32 v47, v38, v39
	s_mov_b64 exec, s[2:3]
	global_store_dword v46, v47, s[14:15] offset:-4096
	s_mov_b64 exec, -1
	s_waitcnt lgkmcnt(0)
	v_pk_mul_f32 v[40:41], v[40:41], v[42:43]
	v_pk_mul_f32 v[44:45], v[64:65], v[40:41] op_sel_hi:[1,0]
	v_pk_fma_f32 v[6:7], v[44:45], v[48:49], v[6:7] op_sel_hi:[1,0,1]
	v_pk_mul_f32 v[38:39], v[6:7], v[48:49] op_sel:[0,1] op_sel_hi:[1,1]
	v_pk_fma_f32 v[8:9], v[44:45], v[50:51], v[8:9] op_sel_hi:[1,0,1]
	v_pk_fma_f32 v[38:39], v[8:9], v[50:51], v[38:39] op_sel:[0,1,0] op_sel_hi:[1,1,1]
	v_pk_fma_f32 v[10:11], v[44:45], v[52:53], v[10:11] op_sel_hi:[1,0,1]
	v_pk_fma_f32 v[38:39], v[10:11], v[52:53], v[38:39] op_sel:[0,1,0] op_sel_hi:[1,1,1]
	v_pk_fma_f32 v[12:13], v[44:45], v[54:55], v[12:13] op_sel_hi:[1,0,1]
	v_pk_fma_f32 v[38:39], v[12:13], v[54:55], v[38:39] op_sel:[0,1,0] op_sel_hi:[1,1,1]
	v_pk_fma_f32 v[14:15], v[44:45], v[56:57], v[14:15] op_sel_hi:[1,0,1]
	v_pk_fma_f32 v[38:39], v[14:15], v[56:57], v[38:39] op_sel:[0,1,0] op_sel_hi:[1,1,1]
	v_pk_fma_f32 v[16:17], v[44:45], v[58:59], v[16:17] op_sel_hi:[1,0,1]
	v_pk_fma_f32 v[38:39], v[16:17], v[58:59], v[38:39] op_sel:[0,1,0] op_sel_hi:[1,1,1]
	v_pk_fma_f32 v[18:19], v[44:45], v[60:61], v[18:19] op_sel_hi:[1,0,1]
	v_pk_fma_f32 v[38:39], v[18:19], v[60:61], v[38:39] op_sel:[0,1,0] op_sel_hi:[1,1,1]
	v_pk_fma_f32 v[20:21], v[44:45], v[62:63], v[20:21] op_sel_hi:[1,0,1]
	v_pk_fma_f32 v[38:39], v[20:21], v[62:63], v[38:39] op_sel:[0,1,0] op_sel_hi:[1,1,1]
	s_add_u32 s14, s14, 0x1000
	s_addc_u32 s15, s15, 0
	v_add_f32_dpp v38, v38, v38 row_ror:8 row_mask:0xf bank_mask:0x3 bound_ctrl:1
	v_add_f32_dpp v38, v39, v39 row_ror:8 row_mask:0xf bank_mask:0xc bound_ctrl:1
	ds_read_b128 v[66:69], v22 offset:11264
	ds_read_b128 v[70:73], v22 offset:11520
	v_add_f32_dpp v38, v38, v38 row_half_mirror row_mask:0xf bank_mask:0xf bound_ctrl:1
	ds_read_b128 v[74:77], v22 offset:11776
	ds_read_b128 v[78:81], v22 offset:12032
	v_add_f32_dpp v38, v38, v38 quad_perm:[1,0,3,2] row_mask:0xf bank_mask:0xf bound_ctrl:1
	ds_read_b64 v[82:83], v23 offset:21248
	s_nop 0
	v_add_f32_dpp v38, v38, v38 quad_perm:[2,3,0,1] row_mask:0xf bank_mask:0xf bound_ctrl:1
	s_nop 1
	v_mov_b32_dpp v39, v38 row_ror:8 row_mask:0xf bank_mask:0xf bound_ctrl:1
	v_pk_mul_f32 v[38:39], v[38:39], v[40:41] op_sel:[0,1] op_sel_hi:[1,1]
	v_cvt_pk_bf16_f32 v47, v38, v39
	s_mov_b64 exec, s[2:3]
	global_store_dword v46, v47, s[14:15] offset:-4096
	s_mov_b64 exec, -1
	s_waitcnt lgkmcnt(0)
	v_pk_mul_f32 v[40:41], v[40:41], v[42:43]
	v_pk_mul_f32 v[44:45], v[82:83], v[40:41] op_sel_hi:[1,0]
	v_pk_fma_f32 v[6:7], v[44:45], v[66:67], v[6:7] op_sel_hi:[1,0,1]
	v_pk_mul_f32 v[38:39], v[6:7], v[66:67] op_sel:[0,1] op_sel_hi:[1,1]
	v_pk_fma_f32 v[8:9], v[44:45], v[68:69], v[8:9] op_sel_hi:[1,0,1]
	v_pk_fma_f32 v[38:39], v[8:9], v[68:69], v[38:39] op_sel:[0,1,0] op_sel_hi:[1,1,1]
	v_pk_fma_f32 v[10:11], v[44:45], v[70:71], v[10:11] op_sel_hi:[1,0,1]
	v_pk_fma_f32 v[38:39], v[10:11], v[70:71], v[38:39] op_sel:[0,1,0] op_sel_hi:[1,1,1]
	v_pk_fma_f32 v[12:13], v[44:45], v[72:73], v[12:13] op_sel_hi:[1,0,1]
	v_pk_fma_f32 v[38:39], v[12:13], v[72:73], v[38:39] op_sel:[0,1,0] op_sel_hi:[1,1,1]
	v_pk_fma_f32 v[14:15], v[44:45], v[74:75], v[14:15] op_sel_hi:[1,0,1]
	v_pk_fma_f32 v[38:39], v[14:15], v[74:75], v[38:39] op_sel:[0,1,0] op_sel_hi:[1,1,1]
	v_pk_fma_f32 v[16:17], v[44:45], v[76:77], v[16:17] op_sel_hi:[1,0,1]
	v_pk_fma_f32 v[38:39], v[16:17], v[76:77], v[38:39] op_sel:[0,1,0] op_sel_hi:[1,1,1]
	v_pk_fma_f32 v[18:19], v[44:45], v[78:79], v[18:19] op_sel_hi:[1,0,1]
	v_pk_fma_f32 v[38:39], v[18:19], v[78:79], v[38:39] op_sel:[0,1,0] op_sel_hi:[1,1,1]
	v_pk_fma_f32 v[20:21], v[44:45], v[80:81], v[20:21] op_sel_hi:[1,0,1]
	v_pk_fma_f32 v[38:39], v[20:21], v[80:81], v[38:39] op_sel:[0,1,0] op_sel_hi:[1,1,1]
	s_add_u32 s14, s14, 0x1000
	s_addc_u32 s15, s15, 0
	v_add_f32_dpp v38, v38, v38 row_ror:8 row_mask:0xf bank_mask:0x3 bound_ctrl:1
	v_add_f32_dpp v38, v39, v39 row_ror:8 row_mask:0xf bank_mask:0xc bound_ctrl:1
	ds_read_b128 v[48:51], v22 offset:12288
	ds_read_b128 v[52:55], v22 offset:12544
	v_add_f32_dpp v38, v38, v38 row_half_mirror row_mask:0xf bank_mask:0xf bound_ctrl:1
	ds_read_b128 v[56:59], v22 offset:12800
	ds_read_b128 v[60:63], v22 offset:13056
	v_add_f32_dpp v38, v38, v38 quad_perm:[1,0,3,2] row_mask:0xf bank_mask:0xf bound_ctrl:1
	ds_read_b64 v[64:65], v23 offset:21504
	s_nop 0
	v_add_f32_dpp v38, v38, v38 quad_perm:[2,3,0,1] row_mask:0xf bank_mask:0xf bound_ctrl:1
	s_nop 1
	v_mov_b32_dpp v39, v38 row_ror:8 row_mask:0xf bank_mask:0xf bound_ctrl:1
	v_pk_mul_f32 v[38:39], v[38:39], v[40:41] op_sel:[0,1] op_sel_hi:[1,1]
	v_cvt_pk_bf16_f32 v47, v38, v39
	s_mov_b64 exec, s[2:3]
	global_store_dword v46, v47, s[14:15] offset:-4096
	s_mov_b64 exec, -1
	s_waitcnt lgkmcnt(0)
	v_pk_mul_f32 v[40:41], v[40:41], v[42:43]
	v_pk_mul_f32 v[44:45], v[64:65], v[40:41] op_sel_hi:[1,0]
	v_pk_fma_f32 v[6:7], v[44:45], v[48:49], v[6:7] op_sel_hi:[1,0,1]
	v_pk_mul_f32 v[38:39], v[6:7], v[48:49] op_sel:[0,1] op_sel_hi:[1,1]
	v_pk_fma_f32 v[8:9], v[44:45], v[50:51], v[8:9] op_sel_hi:[1,0,1]
	v_pk_fma_f32 v[38:39], v[8:9], v[50:51], v[38:39] op_sel:[0,1,0] op_sel_hi:[1,1,1]
	v_pk_fma_f32 v[10:11], v[44:45], v[52:53], v[10:11] op_sel_hi:[1,0,1]
	v_pk_fma_f32 v[38:39], v[10:11], v[52:53], v[38:39] op_sel:[0,1,0] op_sel_hi:[1,1,1]
	v_pk_fma_f32 v[12:13], v[44:45], v[54:55], v[12:13] op_sel_hi:[1,0,1]
	v_pk_fma_f32 v[38:39], v[12:13], v[54:55], v[38:39] op_sel:[0,1,0] op_sel_hi:[1,1,1]
	v_pk_fma_f32 v[14:15], v[44:45], v[56:57], v[14:15] op_sel_hi:[1,0,1]
	v_pk_fma_f32 v[38:39], v[14:15], v[56:57], v[38:39] op_sel:[0,1,0] op_sel_hi:[1,1,1]
	v_pk_fma_f32 v[16:17], v[44:45], v[58:59], v[16:17] op_sel_hi:[1,0,1]
	v_pk_fma_f32 v[38:39], v[16:17], v[58:59], v[38:39] op_sel:[0,1,0] op_sel_hi:[1,1,1]
	v_pk_fma_f32 v[18:19], v[44:45], v[60:61], v[18:19] op_sel_hi:[1,0,1]
	v_pk_fma_f32 v[38:39], v[18:19], v[60:61], v[38:39] op_sel:[0,1,0] op_sel_hi:[1,1,1]
	v_pk_fma_f32 v[20:21], v[44:45], v[62:63], v[20:21] op_sel_hi:[1,0,1]
	v_pk_fma_f32 v[38:39], v[20:21], v[62:63], v[38:39] op_sel:[0,1,0] op_sel_hi:[1,1,1]
	s_add_u32 s14, s14, 0x1000
	s_addc_u32 s15, s15, 0
	v_add_f32_dpp v38, v38, v38 row_ror:8 row_mask:0xf bank_mask:0x3 bound_ctrl:1
	v_add_f32_dpp v38, v39, v39 row_ror:8 row_mask:0xf bank_mask:0xc bound_ctrl:1
	ds_read_b128 v[66:69], v22 offset:13312
	ds_read_b128 v[70:73], v22 offset:13568
	v_add_f32_dpp v38, v38, v38 row_half_mirror row_mask:0xf bank_mask:0xf bound_ctrl:1
	ds_read_b128 v[74:77], v22 offset:13824
	ds_read_b128 v[78:81], v22 offset:14080
	v_add_f32_dpp v38, v38, v38 quad_perm:[1,0,3,2] row_mask:0xf bank_mask:0xf bound_ctrl:1
	ds_read_b64 v[82:83], v23 offset:21760
	s_nop 0
	v_add_f32_dpp v38, v38, v38 quad_perm:[2,3,0,1] row_mask:0xf bank_mask:0xf bound_ctrl:1
	s_nop 1
	v_mov_b32_dpp v39, v38 row_ror:8 row_mask:0xf bank_mask:0xf bound_ctrl:1
	v_pk_mul_f32 v[38:39], v[38:39], v[40:41] op_sel:[0,1] op_sel_hi:[1,1]
	v_cvt_pk_bf16_f32 v47, v38, v39
	s_mov_b64 exec, s[2:3]
	global_store_dword v46, v47, s[14:15] offset:-4096
	s_mov_b64 exec, -1
	s_waitcnt lgkmcnt(0)
	v_pk_mul_f32 v[40:41], v[40:41], v[42:43]
	v_pk_mul_f32 v[44:45], v[82:83], v[40:41] op_sel_hi:[1,0]
	v_pk_fma_f32 v[6:7], v[44:45], v[66:67], v[6:7] op_sel_hi:[1,0,1]
	v_pk_mul_f32 v[38:39], v[6:7], v[66:67] op_sel:[0,1] op_sel_hi:[1,1]
	v_pk_fma_f32 v[8:9], v[44:45], v[68:69], v[8:9] op_sel_hi:[1,0,1]
	v_pk_fma_f32 v[38:39], v[8:9], v[68:69], v[38:39] op_sel:[0,1,0] op_sel_hi:[1,1,1]
	v_pk_fma_f32 v[10:11], v[44:45], v[70:71], v[10:11] op_sel_hi:[1,0,1]
	v_pk_fma_f32 v[38:39], v[10:11], v[70:71], v[38:39] op_sel:[0,1,0] op_sel_hi:[1,1,1]
	v_pk_fma_f32 v[12:13], v[44:45], v[72:73], v[12:13] op_sel_hi:[1,0,1]
	v_pk_fma_f32 v[38:39], v[12:13], v[72:73], v[38:39] op_sel:[0,1,0] op_sel_hi:[1,1,1]
	v_pk_fma_f32 v[14:15], v[44:45], v[74:75], v[14:15] op_sel_hi:[1,0,1]
	v_pk_fma_f32 v[38:39], v[14:15], v[74:75], v[38:39] op_sel:[0,1,0] op_sel_hi:[1,1,1]
	v_pk_fma_f32 v[16:17], v[44:45], v[76:77], v[16:17] op_sel_hi:[1,0,1]
	v_pk_fma_f32 v[38:39], v[16:17], v[76:77], v[38:39] op_sel:[0,1,0] op_sel_hi:[1,1,1]
	v_pk_fma_f32 v[18:19], v[44:45], v[78:79], v[18:19] op_sel_hi:[1,0,1]
	v_pk_fma_f32 v[38:39], v[18:19], v[78:79], v[38:39] op_sel:[0,1,0] op_sel_hi:[1,1,1]
	v_pk_fma_f32 v[20:21], v[44:45], v[80:81], v[20:21] op_sel_hi:[1,0,1]
	v_pk_fma_f32 v[38:39], v[20:21], v[80:81], v[38:39] op_sel:[0,1,0] op_sel_hi:[1,1,1]
	s_add_u32 s14, s14, 0x1000
	s_addc_u32 s15, s15, 0
	v_add_f32_dpp v38, v38, v38 row_ror:8 row_mask:0xf bank_mask:0x3 bound_ctrl:1
	v_add_f32_dpp v38, v39, v39 row_ror:8 row_mask:0xf bank_mask:0xc bound_ctrl:1
	ds_read_b128 v[48:51], v22 offset:14336
	ds_read_b128 v[52:55], v22 offset:14592
	v_add_f32_dpp v38, v38, v38 row_half_mirror row_mask:0xf bank_mask:0xf bound_ctrl:1
	ds_read_b128 v[56:59], v22 offset:14848
	ds_read_b128 v[60:63], v22 offset:15104
	v_add_f32_dpp v38, v38, v38 quad_perm:[1,0,3,2] row_mask:0xf bank_mask:0xf bound_ctrl:1
	ds_read_b64 v[64:65], v23 offset:22016
	s_nop 0
	v_add_f32_dpp v38, v38, v38 quad_perm:[2,3,0,1] row_mask:0xf bank_mask:0xf bound_ctrl:1
	s_nop 1
	v_mov_b32_dpp v39, v38 row_ror:8 row_mask:0xf bank_mask:0xf bound_ctrl:1
	v_pk_mul_f32 v[38:39], v[38:39], v[40:41] op_sel:[0,1] op_sel_hi:[1,1]
	v_cvt_pk_bf16_f32 v47, v38, v39
	s_mov_b64 exec, s[2:3]
	global_store_dword v46, v47, s[14:15] offset:-4096
	s_mov_b64 exec, -1
	s_waitcnt lgkmcnt(0)
	v_pk_mul_f32 v[40:41], v[40:41], v[42:43]
	v_pk_mul_f32 v[44:45], v[64:65], v[40:41] op_sel_hi:[1,0]
	v_pk_fma_f32 v[6:7], v[44:45], v[48:49], v[6:7] op_sel_hi:[1,0,1]
	v_pk_mul_f32 v[38:39], v[6:7], v[48:49] op_sel:[0,1] op_sel_hi:[1,1]
	v_pk_fma_f32 v[8:9], v[44:45], v[50:51], v[8:9] op_sel_hi:[1,0,1]
	v_pk_fma_f32 v[38:39], v[8:9], v[50:51], v[38:39] op_sel:[0,1,0] op_sel_hi:[1,1,1]
	v_pk_fma_f32 v[10:11], v[44:45], v[52:53], v[10:11] op_sel_hi:[1,0,1]
	v_pk_fma_f32 v[38:39], v[10:11], v[52:53], v[38:39] op_sel:[0,1,0] op_sel_hi:[1,1,1]
	v_pk_fma_f32 v[12:13], v[44:45], v[54:55], v[12:13] op_sel_hi:[1,0,1]
	v_pk_fma_f32 v[38:39], v[12:13], v[54:55], v[38:39] op_sel:[0,1,0] op_sel_hi:[1,1,1]
	v_pk_fma_f32 v[14:15], v[44:45], v[56:57], v[14:15] op_sel_hi:[1,0,1]
	v_pk_fma_f32 v[38:39], v[14:15], v[56:57], v[38:39] op_sel:[0,1,0] op_sel_hi:[1,1,1]
	v_pk_fma_f32 v[16:17], v[44:45], v[58:59], v[16:17] op_sel_hi:[1,0,1]
	v_pk_fma_f32 v[38:39], v[16:17], v[58:59], v[38:39] op_sel:[0,1,0] op_sel_hi:[1,1,1]
	v_pk_fma_f32 v[18:19], v[44:45], v[60:61], v[18:19] op_sel_hi:[1,0,1]
	v_pk_fma_f32 v[38:39], v[18:19], v[60:61], v[38:39] op_sel:[0,1,0] op_sel_hi:[1,1,1]
	v_pk_fma_f32 v[20:21], v[44:45], v[62:63], v[20:21] op_sel_hi:[1,0,1]
	v_pk_fma_f32 v[38:39], v[20:21], v[62:63], v[38:39] op_sel:[0,1,0] op_sel_hi:[1,1,1]
	s_add_u32 s14, s14, 0x1000
	s_addc_u32 s15, s15, 0
	v_add_f32_dpp v38, v38, v38 row_ror:8 row_mask:0xf bank_mask:0x3 bound_ctrl:1
	v_add_f32_dpp v38, v39, v39 row_ror:8 row_mask:0xf bank_mask:0xc bound_ctrl:1
	ds_read_b128 v[66:69], v22 offset:15360
	ds_read_b128 v[70:73], v22 offset:15616
	v_add_f32_dpp v38, v38, v38 row_half_mirror row_mask:0xf bank_mask:0xf bound_ctrl:1
	ds_read_b128 v[74:77], v22 offset:15872
	ds_read_b128 v[78:81], v22 offset:16128
	v_add_f32_dpp v38, v38, v38 quad_perm:[1,0,3,2] row_mask:0xf bank_mask:0xf bound_ctrl:1
	ds_read_b64 v[82:83], v23 offset:22272
	s_nop 0
	v_add_f32_dpp v38, v38, v38 quad_perm:[2,3,0,1] row_mask:0xf bank_mask:0xf bound_ctrl:1
	s_nop 1
	v_mov_b32_dpp v39, v38 row_ror:8 row_mask:0xf bank_mask:0xf bound_ctrl:1
	v_pk_mul_f32 v[38:39], v[38:39], v[40:41] op_sel:[0,1] op_sel_hi:[1,1]
	v_cvt_pk_bf16_f32 v47, v38, v39
	s_mov_b64 exec, s[2:3]
	global_store_dword v46, v47, s[14:15] offset:-4096
	s_mov_b64 exec, -1
	s_waitcnt lgkmcnt(0)
	v_pk_mul_f32 v[40:41], v[40:41], v[42:43]
	v_pk_mul_f32 v[44:45], v[82:83], v[40:41] op_sel_hi:[1,0]
	v_pk_fma_f32 v[6:7], v[44:45], v[66:67], v[6:7] op_sel_hi:[1,0,1]
	v_pk_mul_f32 v[38:39], v[6:7], v[66:67] op_sel:[0,1] op_sel_hi:[1,1]
	v_pk_fma_f32 v[8:9], v[44:45], v[68:69], v[8:9] op_sel_hi:[1,0,1]
	v_pk_fma_f32 v[38:39], v[8:9], v[68:69], v[38:39] op_sel:[0,1,0] op_sel_hi:[1,1,1]
	v_pk_fma_f32 v[10:11], v[44:45], v[70:71], v[10:11] op_sel_hi:[1,0,1]
	v_pk_fma_f32 v[38:39], v[10:11], v[70:71], v[38:39] op_sel:[0,1,0] op_sel_hi:[1,1,1]
	v_pk_fma_f32 v[12:13], v[44:45], v[72:73], v[12:13] op_sel_hi:[1,0,1]
	v_pk_fma_f32 v[38:39], v[12:13], v[72:73], v[38:39] op_sel:[0,1,0] op_sel_hi:[1,1,1]
	v_pk_fma_f32 v[14:15], v[44:45], v[74:75], v[14:15] op_sel_hi:[1,0,1]
	v_pk_fma_f32 v[38:39], v[14:15], v[74:75], v[38:39] op_sel:[0,1,0] op_sel_hi:[1,1,1]
	v_pk_fma_f32 v[16:17], v[44:45], v[76:77], v[16:17] op_sel_hi:[1,0,1]
	v_pk_fma_f32 v[38:39], v[16:17], v[76:77], v[38:39] op_sel:[0,1,0] op_sel_hi:[1,1,1]
	v_pk_fma_f32 v[18:19], v[44:45], v[78:79], v[18:19] op_sel_hi:[1,0,1]
	v_pk_fma_f32 v[38:39], v[18:19], v[78:79], v[38:39] op_sel:[0,1,0] op_sel_hi:[1,1,1]
	v_pk_fma_f32 v[20:21], v[44:45], v[80:81], v[20:21] op_sel_hi:[1,0,1]
	v_pk_fma_f32 v[38:39], v[20:21], v[80:81], v[38:39] op_sel:[0,1,0] op_sel_hi:[1,1,1]
	s_add_u32 s14, s14, 0x1000
	s_addc_u32 s15, s15, 0
	v_add_f32_dpp v38, v38, v38 row_ror:8 row_mask:0xf bank_mask:0x3 bound_ctrl:1
	v_add_f32_dpp v38, v39, v39 row_ror:8 row_mask:0xf bank_mask:0xc bound_ctrl:1
	ds_read_b128 v[48:51], v24 offset:8192
	ds_read_b128 v[52:55], v24 offset:8448
	v_add_f32_dpp v38, v38, v38 row_half_mirror row_mask:0xf bank_mask:0xf bound_ctrl:1
	ds_read_b128 v[56:59], v24 offset:8704
	ds_read_b128 v[60:63], v24 offset:8960
	v_add_f32_dpp v38, v38, v38 quad_perm:[1,0,3,2] row_mask:0xf bank_mask:0xf bound_ctrl:1
	ds_read_b64 v[64:65], v25 offset:20480
	s_nop 0
	v_add_f32_dpp v38, v38, v38 quad_perm:[2,3,0,1] row_mask:0xf bank_mask:0xf bound_ctrl:1
	s_nop 1
	v_mov_b32_dpp v39, v38 row_ror:8 row_mask:0xf bank_mask:0xf bound_ctrl:1
	v_pk_mul_f32 v[38:39], v[38:39], v[40:41] op_sel:[0,1] op_sel_hi:[1,1]
	v_cvt_pk_bf16_f32 v47, v38, v39
	s_mov_b64 exec, s[2:3]
	global_store_dword v46, v47, s[14:15] offset:-4096
	s_mov_b64 exec, -1
	s_waitcnt vmcnt(8)
	v_lshlrev_b32_e32 v108, 16, v84
	v_lshlrev_b32_e32 v109, 16, v85
	v_and_b32_e32 v110, s17, v84
	v_and_b32_e32 v111, s17, v85
	v_lshlrev_b32_e32 v112, 16, v86
	v_lshlrev_b32_e32 v113, 16, v87
	v_and_b32_e32 v114, s17, v86
	v_and_b32_e32 v115, s17, v87
	v_lshlrev_b32_e32 v116, 16, v88
	v_and_b32_e32 v117, s17, v88
	ds_write_b128 v26, v[108:111] offset:0
	ds_write_b128 v26, v[112:115] offset:8192
	ds_write_b64 v27, v[90:91]
	ds_write_b64 v28, v[116:117]
	s_mov_b32 s0, s20
	s_mov_b32 s20, s21
	s_mov_b32 s21, s22
	s_mov_b32 s22, s0
	v_mov_b32_e32 v22, v24
	v_mov_b32_e32 v23, v25
	v_add_u32_e32 v24, s21, v2
	v_add_u32_e32 v25, s21, v3
	v_add_u32_e32 v26, s22, v29
	v_add_u32_e32 v27, s22, v30
	v_add_u32_e32 v28, s22, v31
	s_waitcnt lgkmcnt(0)
	s_barrier
	s_add_i32 s16, s16, 8
	s_cmpk_lt_u32 s16, 0x800
	s_cbranch_scc1 .Lret2_loop
	v_readlane_b32 s0, v255, 18
	v_readlane_b32 s1, v255, 19
	s_load_dwordx2 s[2:3], s[0:1], 0xe8
	s_lshr_b32 s0, s23, 5
	s_lshl_b32 s4, s0, 17
	s_add_u32 s4, s4, 78430464
	v_lshl_add_u32 v42, v46, 1, v4
	s_waitcnt lgkmcnt(0)
	s_add_u32 s2, s2, s4
	s_addc_u32 s3, s3, 0
	v_pk_mul_f32 v[6:7], v[6:7], v[40:41] op_sel:[0,1] op_sel_hi:[1,1]
	v_pk_mul_f32 v[8:9], v[8:9], v[40:41] op_sel:[0,1] op_sel_hi:[1,1]
	v_pk_mul_f32 v[10:11], v[10:11], v[40:41] op_sel:[0,1] op_sel_hi:[1,1]
	v_pk_mul_f32 v[12:13], v[12:13], v[40:41] op_sel:[0,1] op_sel_hi:[1,1]
	v_pk_mul_f32 v[14:15], v[14:15], v[40:41] op_sel:[0,1] op_sel_hi:[1,1]
	v_pk_mul_f32 v[16:17], v[16:17], v[40:41] op_sel:[0,1] op_sel_hi:[1,1]
	v_pk_mul_f32 v[18:19], v[18:19], v[40:41] op_sel:[0,1] op_sel_hi:[1,1]
	v_pk_mul_f32 v[20:21], v[20:21], v[40:41] op_sel:[0,1] op_sel_hi:[1,1]
	global_store_dwordx2 v42, v[6:7], s[2:3] offset:0
	global_store_dwordx2 v42, v[8:9], s[2:3] offset:1024
	global_store_dwordx2 v42, v[10:11], s[2:3] offset:2048
	global_store_dwordx2 v42, v[12:13], s[2:3] offset:3072
	s_add_u32 s2, s2, 0x1000
	s_addc_u32 s3, s3, 0
	global_store_dwordx2 v42, v[14:15], s[2:3] offset:0
	global_store_dwordx2 v42, v[16:17], s[2:3] offset:1024
	global_store_dwordx2 v42, v[18:19], s[2:3] offset:2048
	global_store_dwordx2 v42, v[20:21], s[2:3] offset:3072
	s_add_i32 s23, s23, s19
	s_waitcnt vmcnt(0)
	s_cmpk_lt_i32 s23, 0x400
	s_cbranch_scc1 .Lret2_item
	s_branch .LBB0_57

.Lgla2_loop:
	global_load_dword v110, v32, s[10:11]
	global_load_dword v111, v32, s[10:11] offset:-1024
	global_load_dword v112, v33, s[10:11]
	global_load_dword v113, v33, s[10:11] offset:-1024
	global_load_dword v114, v34, s[10:11]
	global_load_dword v116, v35, s[12:13]
	global_load_dword v117, v35, s[12:13] offset:4
	s_add_u32 s10, s10, 0x18000
	s_addc_u32 s11, s11, 0
	s_add_u32 s12, s12, 0x4000
	s_addc_u32 s13, s13, 0
	s_waitcnt lgkmcnt(0)
	v_pk_mul_f32 v[42:43], v[72:73], v[48:49] op_sel_hi:[1,0]
	v_pk_fma_f32 v[6:7], v[6:7], v[64:65], v[42:43] op_sel:[0,0,0] op_sel_hi:[1,0,1]
	v_pk_mul_f32 v[38:39], v[6:7], v[48:49] op_sel:[0,1] op_sel_hi:[1,1]
	v_pk_mul_f32 v[44:45], v[72:73], v[50:51] op_sel_hi:[1,0]
	v_pk_fma_f32 v[8:9], v[8:9], v[64:65], v[44:45] op_sel:[0,1,0] op_sel_hi:[1,1,1]
	v_pk_fma_f32 v[38:39], v[8:9], v[50:51], v[38:39] op_sel:[0,1,0] op_sel_hi:[1,1,1]
	v_pk_mul_f32 v[42:43], v[72:73], v[52:53] op_sel_hi:[1,0]
	v_pk_fma_f32 v[10:11], v[10:11], v[66:67], v[42:43] op_sel:[0,0,0] op_sel_hi:[1,0,1]
	v_pk_fma_f32 v[38:39], v[10:11], v[52:53], v[38:39] op_sel:[0,1,0] op_sel_hi:[1,1,1]
	v_pk_mul_f32 v[44:45], v[72:73], v[54:55] op_sel_hi:[1,0]
	v_pk_fma_f32 v[12:13], v[12:13], v[66:67], v[44:45] op_sel:[0,1,0] op_sel_hi:[1,1,1]
	v_pk_fma_f32 v[38:39], v[12:13], v[54:55], v[38:39] op_sel:[0,1,0] op_sel_hi:[1,1,1]
	v_pk_mul_f32 v[42:43], v[72:73], v[56:57] op_sel_hi:[1,0]
	v_pk_fma_f32 v[14:15], v[14:15], v[68:69], v[42:43] op_sel:[0,0,0] op_sel_hi:[1,0,1]
	v_pk_fma_f32 v[38:39], v[14:15], v[56:57], v[38:39] op_sel:[0,1,0] op_sel_hi:[1,1,1]
	v_pk_mul_f32 v[44:45], v[72:73], v[58:59] op_sel_hi:[1,0]
	v_pk_fma_f32 v[16:17], v[16:17], v[68:69], v[44:45] op_sel:[0,1,0] op_sel_hi:[1,1,1]
	v_pk_fma_f32 v[38:39], v[16:17], v[58:59], v[38:39] op_sel:[0,1,0] op_sel_hi:[1,1,1]
	v_pk_mul_f32 v[42:43], v[72:73], v[60:61] op_sel_hi:[1,0]
	v_pk_fma_f32 v[18:19], v[18:19], v[70:71], v[42:43] op_sel:[0,0,0] op_sel_hi:[1,0,1]
	v_pk_fma_f32 v[38:39], v[18:19], v[60:61], v[38:39] op_sel:[0,1,0] op_sel_hi:[1,1,1]
	v_pk_mul_f32 v[44:45], v[72:73], v[62:63] op_sel_hi:[1,0]
	v_pk_fma_f32 v[20:21], v[20:21], v[70:71], v[44:45] op_sel:[0,1,0] op_sel_hi:[1,1,1]
	v_pk_fma_f32 v[38:39], v[20:21], v[62:63], v[38:39] op_sel:[0,1,0] op_sel_hi:[1,1,1]
	s_add_u32 s14, s14, 0x1000
	s_addc_u32 s15, s15, 0
	v_add_f32_dpp v38, v38, v38 row_ror:8 row_mask:0xf bank_mask:0x3 bound_ctrl:1
	v_add_f32_dpp v38, v39, v39 row_ror:8 row_mask:0xf bank_mask:0xc bound_ctrl:1
	ds_read_b128 v[80:83], v22 offset:1024
	ds_read_b128 v[84:87], v22 offset:1280
	v_add_f32_dpp v38, v38, v38 row_half_mirror row_mask:0xf bank_mask:0xf bound_ctrl:1
	ds_read_b128 v[88:91], v22 offset:1536
	ds_read_b128 v[92:95], v22 offset:1792
	v_add_f32_dpp v38, v38, v38 quad_perm:[1,0,3,2] row_mask:0xf bank_mask:0xf bound_ctrl:1
	ds_read_b128 v[96:99], v22 offset:16896
	ds_read_b128 v[100:103], v22 offset:17152
	v_add_f32_dpp v38, v38, v38 quad_perm:[2,3,0,1] row_mask:0xf bank_mask:0xf bound_ctrl:1
	ds_read_b64 v[104:105], v23 offset:20736
	s_nop 0
	v_mov_b32_dpp v39, v38 row_ror:8 row_mask:0xf bank_mask:0xf bound_ctrl:1
	v_pk_mul_f32 v[38:39], v[38:39], v[40:41] op_sel_hi:[1,0]
	v_cvt_pk_bf16_f32 v47, v38, v39
	s_mov_b64 exec, s[2:3]
	global_store_dword v46, v47, s[14:15] offset:-4096
	s_mov_b64 exec, -1
	s_waitcnt lgkmcnt(0)
	v_pk_mul_f32 v[42:43], v[104:105], v[80:81] op_sel_hi:[1,0]
	v_pk_fma_f32 v[6:7], v[6:7], v[96:97], v[42:43] op_sel:[0,0,0] op_sel_hi:[1,0,1]
	v_pk_mul_f32 v[38:39], v[6:7], v[80:81] op_sel:[0,1] op_sel_hi:[1,1]
	v_pk_mul_f32 v[44:45], v[104:105], v[82:83] op_sel_hi:[1,0]
	v_pk_fma_f32 v[8:9], v[8:9], v[96:97], v[44:45] op_sel:[0,1,0] op_sel_hi:[1,1,1]
	v_pk_fma_f32 v[38:39], v[8:9], v[82:83], v[38:39] op_sel:[0,1,0] op_sel_hi:[1,1,1]
	v_pk_mul_f32 v[42:43], v[104:105], v[84:85] op_sel_hi:[1,0]
	v_pk_fma_f32 v[10:11], v[10:11], v[98:99], v[42:43] op_sel:[0,0,0] op_sel_hi:[1,0,1]
	v_pk_fma_f32 v[38:39], v[10:11], v[84:85], v[38:39] op_sel:[0,1,0] op_sel_hi:[1,1,1]
	v_pk_mul_f32 v[44:45], v[104:105], v[86:87] op_sel_hi:[1,0]
	v_pk_fma_f32 v[12:13], v[12:13], v[98:99], v[44:45] op_sel:[0,1,0] op_sel_hi:[1,1,1]
	v_pk_fma_f32 v[38:39], v[12:13], v[86:87], v[38:39] op_sel:[0,1,0] op_sel_hi:[1,1,1]
	v_pk_mul_f32 v[42:43], v[104:105], v[88:89] op_sel_hi:[1,0]
	v_pk_fma_f32 v[14:15], v[14:15], v[100:101], v[42:43] op_sel:[0,0,0] op_sel_hi:[1,0,1]
	v_pk_fma_f32 v[38:39], v[14:15], v[88:89], v[38:39] op_sel:[0,1,0] op_sel_hi:[1,1,1]
	v_pk_mul_f32 v[44:45], v[104:105], v[90:91] op_sel_hi:[1,0]
	v_pk_fma_f32 v[16:17], v[16:17], v[100:101], v[44:45] op_sel:[0,1,0] op_sel_hi:[1,1,1]
	v_pk_fma_f32 v[38:39], v[16:17], v[90:91], v[38:39] op_sel:[0,1,0] op_sel_hi:[1,1,1]
	v_pk_mul_f32 v[42:43], v[104:105], v[92:93] op_sel_hi:[1,0]
	v_pk_fma_f32 v[18:19], v[18:19], v[102:103], v[42:43] op_sel:[0,0,0] op_sel_hi:[1,0,1]
	v_pk_fma_f32 v[38:39], v[18:19], v[92:93], v[38:39] op_sel:[0,1,0] op_sel_hi:[1,1,1]
	v_pk_mul_f32 v[44:45], v[104:105], v[94:95] op_sel_hi:[1,0]
	v_pk_fma_f32 v[20:21], v[20:21], v[102:103], v[44:45] op_sel:[0,1,0] op_sel_hi:[1,1,1]
	v_pk_fma_f32 v[38:39], v[20:21], v[94:95], v[38:39] op_sel:[0,1,0] op_sel_hi:[1,1,1]
	s_add_u32 s14, s14, 0x1000
	s_addc_u32 s15, s15, 0
	v_add_f32_dpp v38, v38, v38 row_ror:8 row_mask:0xf bank_mask:0x3 bound_ctrl:1
	v_add_f32_dpp v38, v39, v39 row_ror:8 row_mask:0xf bank_mask:0xc bound_ctrl:1
	ds_read_b128 v[48:51], v22 offset:2048
	ds_read_b128 v[52:55], v22 offset:2304
	v_add_f32_dpp v38, v38, v38 row_half_mirror row_mask:0xf bank_mask:0xf bound_ctrl:1
	ds_read_b128 v[56:59], v22 offset:2560
	ds_read_b128 v[60:63], v22 offset:2816
	v_add_f32_dpp v38, v38, v38 quad_perm:[1,0,3,2] row_mask:0xf bank_mask:0xf bound_ctrl:1
	ds_read_b128 v[64:67], v22 offset:17408
	ds_read_b128 v[68:71], v22 offset:17664
	v_add_f32_dpp v38, v38, v38 quad_perm:[2,3,0,1] row_mask:0xf bank_mask:0xf bound_ctrl:1
	ds_read_b64 v[72:73], v23 offset:20992
	s_nop 0
	v_mov_b32_dpp v39, v38 row_ror:8 row_mask:0xf bank_mask:0xf bound_ctrl:1
	v_pk_mul_f32 v[38:39], v[38:39], v[40:41] op_sel_hi:[1,0]
	v_cvt_pk_bf16_f32 v47, v38, v39
	s_mov_b64 exec, s[2:3]
	global_store_dword v46, v47, s[14:15] offset:-4096
	s_mov_b64 exec, -1
	s_waitcnt lgkmcnt(0)
	v_pk_mul_f32 v[42:43], v[72:73], v[48:49] op_sel_hi:[1,0]
	v_pk_fma_f32 v[6:7], v[6:7], v[64:65], v[42:43] op_sel:[0,0,0] op_sel_hi:[1,0,1]
	v_pk_mul_f32 v[38:39], v[6:7], v[48:49] op_sel:[0,1] op_sel_hi:[1,1]
	v_pk_mul_f32 v[44:45], v[72:73], v[50:51] op_sel_hi:[1,0]
	v_pk_fma_f32 v[8:9], v[8:9], v[64:65], v[44:45] op_sel:[0,1,0] op_sel_hi:[1,1,1]
	v_pk_fma_f32 v[38:39], v[8:9], v[50:51], v[38:39] op_sel:[0,1,0] op_sel_hi:[1,1,1]
	v_pk_mul_f32 v[42:43], v[72:73], v[52:53] op_sel_hi:[1,0]
	v_pk_fma_f32 v[10:11], v[10:11], v[66:67], v[42:43] op_sel:[0,0,0] op_sel_hi:[1,0,1]
	v_pk_fma_f32 v[38:39], v[10:11], v[52:53], v[38:39] op_sel:[0,1,0] op_sel_hi:[1,1,1]
	v_pk_mul_f32 v[44:45], v[72:73], v[54:55] op_sel_hi:[1,0]
	v_pk_fma_f32 v[12:13], v[12:13], v[66:67], v[44:45] op_sel:[0,1,0] op_sel_hi:[1,1,1]
	v_pk_fma_f32 v[38:39], v[12:13], v[54:55], v[38:39] op_sel:[0,1,0] op_sel_hi:[1,1,1]
	v_pk_mul_f32 v[42:43], v[72:73], v[56:57] op_sel_hi:[1,0]
	v_pk_fma_f32 v[14:15], v[14:15], v[68:69], v[42:43] op_sel:[0,0,0] op_sel_hi:[1,0,1]
	v_pk_fma_f32 v[38:39], v[14:15], v[56:57], v[38:39] op_sel:[0,1,0] op_sel_hi:[1,1,1]
	v_pk_mul_f32 v[44:45], v[72:73], v[58:59] op_sel_hi:[1,0]
	v_pk_fma_f32 v[16:17], v[16:17], v[68:69], v[44:45] op_sel:[0,1,0] op_sel_hi:[1,1,1]
	v_pk_fma_f32 v[38:39], v[16:17], v[58:59], v[38:39] op_sel:[0,1,0] op_sel_hi:[1,1,1]
	v_pk_mul_f32 v[42:43], v[72:73], v[60:61] op_sel_hi:[1,0]
	v_pk_fma_f32 v[18:19], v[18:19], v[70:71], v[42:43] op_sel:[0,0,0] op_sel_hi:[1,0,1]
	v_pk_fma_f32 v[38:39], v[18:19], v[60:61], v[38:39] op_sel:[0,1,0] op_sel_hi:[1,1,1]
	v_pk_mul_f32 v[44:45], v[72:73], v[62:63] op_sel_hi:[1,0]
	v_pk_fma_f32 v[20:21], v[20:21], v[70:71], v[44:45] op_sel:[0,1,0] op_sel_hi:[1,1,1]
	v_pk_fma_f32 v[38:39], v[20:21], v[62:63], v[38:39] op_sel:[0,1,0] op_sel_hi:[1,1,1]
	s_add_u32 s14, s14, 0x1000
	s_addc_u32 s15, s15, 0
	v_add_f32_dpp v38, v38, v38 row_ror:8 row_mask:0xf bank_mask:0x3 bound_ctrl:1
	v_add_f32_dpp v38, v39, v39 row_ror:8 row_mask:0xf bank_mask:0xc bound_ctrl:1
	ds_read_b128 v[80:83], v22 offset:3072
	ds_read_b128 v[84:87], v22 offset:3328
	v_add_f32_dpp v38, v38, v38 row_half_mirror row_mask:0xf bank_mask:0xf bound_ctrl:1
	ds_read_b128 v[88:91], v22 offset:3584
	ds_read_b128 v[92:95], v22 offset:3840
	v_add_f32_dpp v38, v38, v38 quad_perm:[1,0,3,2] row_mask:0xf bank_mask:0xf bound_ctrl:1
	ds_read_b128 v[96:99], v22 offset:17920
	ds_read_b128 v[100:103], v22 offset:18176
	v_add_f32_dpp v38, v38, v38 quad_perm:[2,3,0,1] row_mask:0xf bank_mask:0xf bound_ctrl:1
	ds_read_b64 v[104:105], v23 offset:21248
	s_nop 0
	v_mov_b32_dpp v39, v38 row_ror:8 row_mask:0xf bank_mask:0xf bound_ctrl:1
	v_pk_mul_f32 v[38:39], v[38:39], v[40:41] op_sel_hi:[1,0]
	v_cvt_pk_bf16_f32 v47, v38, v39
	s_mov_b64 exec, s[2:3]
	global_store_dword v46, v47, s[14:15] offset:-4096
	s_mov_b64 exec, -1
	s_waitcnt lgkmcnt(0)
	v_pk_mul_f32 v[42:43], v[104:105], v[80:81] op_sel_hi:[1,0]
	v_pk_fma_f32 v[6:7], v[6:7], v[96:97], v[42:43] op_sel:[0,0,0] op_sel_hi:[1,0,1]
	v_pk_mul_f32 v[38:39], v[6:7], v[80:81] op_sel:[0,1] op_sel_hi:[1,1]
	v_pk_mul_f32 v[44:45], v[104:105], v[82:83] op_sel_hi:[1,0]
	v_pk_fma_f32 v[8:9], v[8:9], v[96:97], v[44:45] op_sel:[0,1,0] op_sel_hi:[1,1,1]
	v_pk_fma_f32 v[38:39], v[8:9], v[82:83], v[38:39] op_sel:[0,1,0] op_sel_hi:[1,1,1]
	v_pk_mul_f32 v[42:43], v[104:105], v[84:85] op_sel_hi:[1,0]
	v_pk_fma_f32 v[10:11], v[10:11], v[98:99], v[42:43] op_sel:[0,0,0] op_sel_hi:[1,0,1]
	v_pk_fma_f32 v[38:39], v[10:11], v[84:85], v[38:39] op_sel:[0,1,0] op_sel_hi:[1,1,1]
	v_pk_mul_f32 v[44:45], v[104:105], v[86:87] op_sel_hi:[1,0]
	v_pk_fma_f32 v[12:13], v[12:13], v[98:99], v[44:45] op_sel:[0,1,0] op_sel_hi:[1,1,1]
	v_pk_fma_f32 v[38:39], v[12:13], v[86:87], v[38:39] op_sel:[0,1,0] op_sel_hi:[1,1,1]
	v_pk_mul_f32 v[42:43], v[104:105], v[88:89] op_sel_hi:[1,0]
	v_pk_fma_f32 v[14:15], v[14:15], v[100:101], v[42:43] op_sel:[0,0,0] op_sel_hi:[1,0,1]
	v_pk_fma_f32 v[38:39], v[14:15], v[88:89], v[38:39] op_sel:[0,1,0] op_sel_hi:[1,1,1]
	v_pk_mul_f32 v[44:45], v[104:105], v[90:91] op_sel_hi:[1,0]
	v_pk_fma_f32 v[16:17], v[16:17], v[100:101], v[44:45] op_sel:[0,1,0] op_sel_hi:[1,1,1]
	v_pk_fma_f32 v[38:39], v[16:17], v[90:91], v[38:39] op_sel:[0,1,0] op_sel_hi:[1,1,1]
	v_pk_mul_f32 v[42:43], v[104:105], v[92:93] op_sel_hi:[1,0]
	v_pk_fma_f32 v[18:19], v[18:19], v[102:103], v[42:43] op_sel:[0,0,0] op_sel_hi:[1,0,1]
	v_pk_fma_f32 v[38:39], v[18:19], v[92:93], v[38:39] op_sel:[0,1,0] op_sel_hi:[1,1,1]
	v_pk_mul_f32 v[44:45], v[104:105], v[94:95] op_sel_hi:[1,0]
	v_pk_fma_f32 v[20:21], v[20:21], v[102:103], v[44:45] op_sel:[0,1,0] op_sel_hi:[1,1,1]
	v_pk_fma_f32 v[38:39], v[20:21], v[94:95], v[38:39] op_sel:[0,1,0] op_sel_hi:[1,1,1]
	s_add_u32 s14, s14, 0x1000
	s_addc_u32 s15, s15, 0
	v_add_f32_dpp v38, v38, v38 row_ror:8 row_mask:0xf bank_mask:0x3 bound_ctrl:1
	v_add_f32_dpp v38, v39, v39 row_ror:8 row_mask:0xf bank_mask:0xc bound_ctrl:1
	ds_read_b128 v[48:51], v22 offset:4096
	ds_read_b128 v[52:55], v22 offset:4352
	v_add_f32_dpp v38, v38, v38 row_half_mirror row_mask:0xf bank_mask:0xf bound_ctrl:1
	ds_read_b128 v[56:59], v22 offset:4608
	ds_read_b128 v[60:63], v22 offset:4864
	v_add_f32_dpp v38, v38, v38 quad_perm:[1,0,3,2] row_mask:0xf bank_mask:0xf bound_ctrl:1
	ds_read_b128 v[64:67], v22 offset:18432
	ds_read_b128 v[68:71], v22 offset:18688
	v_add_f32_dpp v38, v38, v38 quad_perm:[2,3,0,1] row_mask:0xf bank_mask:0xf bound_ctrl:1
	ds_read_b64 v[72:73], v23 offset:21504
	s_nop 0
	v_mov_b32_dpp v39, v38 row_ror:8 row_mask:0xf bank_mask:0xf bound_ctrl:1
	v_pk_mul_f32 v[38:39], v[38:39], v[40:41] op_sel_hi:[1,0]
	v_cvt_pk_bf16_f32 v47, v38, v39
	s_mov_b64 exec, s[2:3]
	global_store_dword v46, v47, s[14:15] offset:-4096
	s_mov_b64 exec, -1
	s_waitcnt lgkmcnt(0)
	v_pk_mul_f32 v[42:43], v[72:73], v[48:49] op_sel_hi:[1,0]
	v_pk_fma_f32 v[6:7], v[6:7], v[64:65], v[42:43] op_sel:[0,0,0] op_sel_hi:[1,0,1]
	v_pk_mul_f32 v[38:39], v[6:7], v[48:49] op_sel:[0,1] op_sel_hi:[1,1]
	v_pk_mul_f32 v[44:45], v[72:73], v[50:51] op_sel_hi:[1,0]
	v_pk_fma_f32 v[8:9], v[8:9], v[64:65], v[44:45] op_sel:[0,1,0] op_sel_hi:[1,1,1]
	v_pk_fma_f32 v[38:39], v[8:9], v[50:51], v[38:39] op_sel:[0,1,0] op_sel_hi:[1,1,1]
	v_pk_mul_f32 v[42:43], v[72:73], v[52:53] op_sel_hi:[1,0]
	v_pk_fma_f32 v[10:11], v[10:11], v[66:67], v[42:43] op_sel:[0,0,0] op_sel_hi:[1,0,1]
	v_pk_fma_f32 v[38:39], v[10:11], v[52:53], v[38:39] op_sel:[0,1,0] op_sel_hi:[1,1,1]
	v_pk_mul_f32 v[44:45], v[72:73], v[54:55] op_sel_hi:[1,0]
	v_pk_fma_f32 v[12:13], v[12:13], v[66:67], v[44:45] op_sel:[0,1,0] op_sel_hi:[1,1,1]
	v_pk_fma_f32 v[38:39], v[12:13], v[54:55], v[38:39] op_sel:[0,1,0] op_sel_hi:[1,1,1]
	v_pk_mul_f32 v[42:43], v[72:73], v[56:57] op_sel_hi:[1,0]
	v_pk_fma_f32 v[14:15], v[14:15], v[68:69], v[42:43] op_sel:[0,0,0] op_sel_hi:[1,0,1]
	v_pk_fma_f32 v[38:39], v[14:15], v[56:57], v[38:39] op_sel:[0,1,0] op_sel_hi:[1,1,1]
	v_pk_mul_f32 v[44:45], v[72:73], v[58:59] op_sel_hi:[1,0]
	v_pk_fma_f32 v[16:17], v[16:17], v[68:69], v[44:45] op_sel:[0,1,0] op_sel_hi:[1,1,1]
	v_pk_fma_f32 v[38:39], v[16:17], v[58:59], v[38:39] op_sel:[0,1,0] op_sel_hi:[1,1,1]
	v_pk_mul_f32 v[42:43], v[72:73], v[60:61] op_sel_hi:[1,0]
	v_pk_fma_f32 v[18:19], v[18:19], v[70:71], v[42:43] op_sel:[0,0,0] op_sel_hi:[1,0,1]
	v_pk_fma_f32 v[38:39], v[18:19], v[60:61], v[38:39] op_sel:[0,1,0] op_sel_hi:[1,1,1]
	v_pk_mul_f32 v[44:45], v[72:73], v[62:63] op_sel_hi:[1,0]
	v_pk_fma_f32 v[20:21], v[20:21], v[70:71], v[44:45] op_sel:[0,1,0] op_sel_hi:[1,1,1]
	v_pk_fma_f32 v[38:39], v[20:21], v[62:63], v[38:39] op_sel:[0,1,0] op_sel_hi:[1,1,1]
	s_add_u32 s14, s14, 0x1000
	s_addc_u32 s15, s15, 0
	v_add_f32_dpp v38, v38, v38 row_ror:8 row_mask:0xf bank_mask:0x3 bound_ctrl:1
	v_add_f32_dpp v38, v39, v39 row_ror:8 row_mask:0xf bank_mask:0xc bound_ctrl:1
	ds_read_b128 v[80:83], v22 offset:5120
	ds_read_b128 v[84:87], v22 offset:5376
	v_add_f32_dpp v38, v38, v38 row_half_mirror row_mask:0xf bank_mask:0xf bound_ctrl:1
	ds_read_b128 v[88:91], v22 offset:5632
	ds_read_b128 v[92:95], v22 offset:5888
	v_add_f32_dpp v38, v38, v38 quad_perm:[1,0,3,2] row_mask:0xf bank_mask:0xf bound_ctrl:1
	ds_read_b128 v[96:99], v22 offset:18944
	ds_read_b128 v[100:103], v22 offset:19200
	v_add_f32_dpp v38, v38, v38 quad_perm:[2,3,0,1] row_mask:0xf bank_mask:0xf bound_ctrl:1
	ds_read_b64 v[104:105], v23 offset:21760
	s_nop 0
	v_mov_b32_dpp v39, v38 row_ror:8 row_mask:0xf bank_mask:0xf bound_ctrl:1
	v_pk_mul_f32 v[38:39], v[38:39], v[40:41] op_sel_hi:[1,0]
	v_cvt_pk_bf16_f32 v47, v38, v39
	s_mov_b64 exec, s[2:3]
	global_store_dword v46, v47, s[14:15] offset:-4096
	s_mov_b64 exec, -1
	s_waitcnt lgkmcnt(0)
	v_pk_mul_f32 v[42:43], v[104:105], v[80:81] op_sel_hi:[1,0]
	v_pk_fma_f32 v[6:7], v[6:7], v[96:97], v[42:43] op_sel:[0,0,0] op_sel_hi:[1,0,1]
	v_pk_mul_f32 v[38:39], v[6:7], v[80:81] op_sel:[0,1] op_sel_hi:[1,1]
	v_pk_mul_f32 v[44:45], v[104:105], v[82:83] op_sel_hi:[1,0]
	v_pk_fma_f32 v[8:9], v[8:9], v[96:97], v[44:45] op_sel:[0,1,0] op_sel_hi:[1,1,1]
	v_pk_fma_f32 v[38:39], v[8:9], v[82:83], v[38:39] op_sel:[0,1,0] op_sel_hi:[1,1,1]
	v_pk_mul_f32 v[42:43], v[104:105], v[84:85] op_sel_hi:[1,0]
	v_pk_fma_f32 v[10:11], v[10:11], v[98:99], v[42:43] op_sel:[0,0,0] op_sel_hi:[1,0,1]
	v_pk_fma_f32 v[38:39], v[10:11], v[84:85], v[38:39] op_sel:[0,1,0] op_sel_hi:[1,1,1]
	v_pk_mul_f32 v[44:45], v[104:105], v[86:87] op_sel_hi:[1,0]
	v_pk_fma_f32 v[12:13], v[12:13], v[98:99], v[44:45] op_sel:[0,1,0] op_sel_hi:[1,1,1]
	v_pk_fma_f32 v[38:39], v[12:13], v[86:87], v[38:39] op_sel:[0,1,0] op_sel_hi:[1,1,1]
	v_pk_mul_f32 v[42:43], v[104:105], v[88:89] op_sel_hi:[1,0]
	v_pk_fma_f32 v[14:15], v[14:15], v[100:101], v[42:43] op_sel:[0,0,0] op_sel_hi:[1,0,1]
	v_pk_fma_f32 v[38:39], v[14:15], v[88:89], v[38:39] op_sel:[0,1,0] op_sel_hi:[1,1,1]
	v_pk_mul_f32 v[44:45], v[104:105], v[90:91] op_sel_hi:[1,0]
	v_pk_fma_f32 v[16:17], v[16:17], v[100:101], v[44:45] op_sel:[0,1,0] op_sel_hi:[1,1,1]
	v_pk_fma_f32 v[38:39], v[16:17], v[90:91], v[38:39] op_sel:[0,1,0] op_sel_hi:[1,1,1]
	v_pk_mul_f32 v[42:43], v[104:105], v[92:93] op_sel_hi:[1,0]
	v_pk_fma_f32 v[18:19], v[18:19], v[102:103], v[42:43] op_sel:[0,0,0] op_sel_hi:[1,0,1]
	v_pk_fma_f32 v[38:39], v[18:19], v[92:93], v[38:39] op_sel:[0,1,0] op_sel_hi:[1,1,1]
	v_pk_mul_f32 v[44:45], v[104:105], v[94:95] op_sel_hi:[1,0]
	v_pk_fma_f32 v[20:21], v[20:21], v[102:103], v[44:45] op_sel:[0,1,0] op_sel_hi:[1,1,1]
	v_pk_fma_f32 v[38:39], v[20:21], v[94:95], v[38:39] op_sel:[0,1,0] op_sel_hi:[1,1,1]
	s_add_u32 s14, s14, 0x1000
	s_addc_u32 s15, s15, 0
	v_add_f32_dpp v38, v38, v38 row_ror:8 row_mask:0xf bank_mask:0x3 bound_ctrl:1
	v_add_f32_dpp v38, v39, v39 row_ror:8 row_mask:0xf bank_mask:0xc bound_ctrl:1
	ds_read_b128 v[48:51], v22 offset:6144
	ds_read_b128 v[52:55], v22 offset:6400
	v_add_f32_dpp v38, v38, v38 row_half_mirror row_mask:0xf bank_mask:0xf bound_ctrl:1
	ds_read_b128 v[56:59], v22 offset:6656
	ds_read_b128 v[60:63], v22 offset:6912
	v_add_f32_dpp v38, v38, v38 quad_perm:[1,0,3,2] row_mask:0xf bank_mask:0xf bound_ctrl:1
	ds_read_b128 v[64:67], v22 offset:19456
	ds_read_b128 v[68:71], v22 offset:19712
	v_add_f32_dpp v38, v38, v38 quad_perm:[2,3,0,1] row_mask:0xf bank_mask:0xf bound_ctrl:1
	ds_read_b64 v[72:73], v23 offset:22016
	s_nop 0
	v_mov_b32_dpp v39, v38 row_ror:8 row_mask:0xf bank_mask:0xf bound_ctrl:1
	v_pk_mul_f32 v[38:39], v[38:39], v[40:41] op_sel_hi:[1,0]
	v_cvt_pk_bf16_f32 v47, v38, v39
	s_mov_b64 exec, s[2:3]
	global_store_dword v46, v47, s[14:15] offset:-4096
	s_mov_b64 exec, -1
	s_waitcnt lgkmcnt(0)
	v_pk_mul_f32 v[42:43], v[72:73], v[48:49] op_sel_hi:[1,0]
	v_pk_fma_f32 v[6:7], v[6:7], v[64:65], v[42:43] op_sel:[0,0,0] op_sel_hi:[1,0,1]
	v_pk_mul_f32 v[38:39], v[6:7], v[48:49] op_sel:[0,1] op_sel_hi:[1,1]
	v_pk_mul_f32 v[44:45], v[72:73], v[50:51] op_sel_hi:[1,0]
	v_pk_fma_f32 v[8:9], v[8:9], v[64:65], v[44:45] op_sel:[0,1,0] op_sel_hi:[1,1,1]
	v_pk_fma_f32 v[38:39], v[8:9], v[50:51], v[38:39] op_sel:[0,1,0] op_sel_hi:[1,1,1]
	v_pk_mul_f32 v[42:43], v[72:73], v[52:53] op_sel_hi:[1,0]
	v_pk_fma_f32 v[10:11], v[10:11], v[66:67], v[42:43] op_sel:[0,0,0] op_sel_hi:[1,0,1]
	v_pk_fma_f32 v[38:39], v[10:11], v[52:53], v[38:39] op_sel:[0,1,0] op_sel_hi:[1,1,1]
	v_pk_mul_f32 v[44:45], v[72:73], v[54:55] op_sel_hi:[1,0]
	v_pk_fma_f32 v[12:13], v[12:13], v[66:67], v[44:45] op_sel:[0,1,0] op_sel_hi:[1,1,1]
	v_pk_fma_f32 v[38:39], v[12:13], v[54:55], v[38:39] op_sel:[0,1,0] op_sel_hi:[1,1,1]
	v_pk_mul_f32 v[42:43], v[72:73], v[56:57] op_sel_hi:[1,0]
	v_pk_fma_f32 v[14:15], v[14:15], v[68:69], v[42:43] op_sel:[0,0,0] op_sel_hi:[1,0,1]
	v_pk_fma_f32 v[38:39], v[14:15], v[56:57], v[38:39] op_sel:[0,1,0] op_sel_hi:[1,1,1]
	v_pk_mul_f32 v[44:45], v[72:73], v[58:59] op_sel_hi:[1,0]
	v_pk_fma_f32 v[16:17], v[16:17], v[68:69], v[44:45] op_sel:[0,1,0] op_sel_hi:[1,1,1]
	v_pk_fma_f32 v[38:39], v[16:17], v[58:59], v[38:39] op_sel:[0,1,0] op_sel_hi:[1,1,1]
	v_pk_mul_f32 v[42:43], v[72:73], v[60:61] op_sel_hi:[1,0]
	v_pk_fma_f32 v[18:19], v[18:19], v[70:71], v[42:43] op_sel:[0,0,0] op_sel_hi:[1,0,1]
	v_pk_fma_f32 v[38:39], v[18:19], v[60:61], v[38:39] op_sel:[0,1,0] op_sel_hi:[1,1,1]
	v_pk_mul_f32 v[44:45], v[72:73], v[62:63] op_sel_hi:[1,0]
	v_pk_fma_f32 v[20:21], v[20:21], v[70:71], v[44:45] op_sel:[0,1,0] op_sel_hi:[1,1,1]
	v_pk_fma_f32 v[38:39], v[20:21], v[62:63], v[38:39] op_sel:[0,1,0] op_sel_hi:[1,1,1]
	s_add_u32 s14, s14, 0x1000
	s_addc_u32 s15, s15, 0
	v_add_f32_dpp v38, v38, v38 row_ror:8 row_mask:0xf bank_mask:0x3 bound_ctrl:1
	v_add_f32_dpp v38, v39, v39 row_ror:8 row_mask:0xf bank_mask:0xc bound_ctrl:1
	ds_read_b128 v[80:83], v22 offset:7168
	ds_read_b128 v[84:87], v22 offset:7424
	v_add_f32_dpp v38, v38, v38 row_half_mirror row_mask:0xf bank_mask:0xf bound_ctrl:1
	ds_read_b128 v[88:91], v22 offset:7680
	ds_read_b128 v[92:95], v22 offset:7936
	v_add_f32_dpp v38, v38, v38 quad_perm:[1,0,3,2] row_mask:0xf bank_mask:0xf bound_ctrl:1
	ds_read_b128 v[96:99], v22 offset:19968
	ds_read_b128 v[100:103], v22 offset:20224
	v_add_f32_dpp v38, v38, v38 quad_perm:[2,3,0,1] row_mask:0xf bank_mask:0xf bound_ctrl:1
	ds_read_b64 v[104:105], v23 offset:22272
	s_nop 0
	v_mov_b32_dpp v39, v38 row_ror:8 row_mask:0xf bank_mask:0xf bound_ctrl:1
	v_pk_mul_f32 v[38:39], v[38:39], v[40:41] op_sel_hi:[1,0]
	v_cvt_pk_bf16_f32 v47, v38, v39
	s_mov_b64 exec, s[2:3]
	global_store_dword v46, v47, s[14:15] offset:-4096
	s_mov_b64 exec, -1
	s_waitcnt lgkmcnt(0)
	v_pk_mul_f32 v[42:43], v[104:105], v[80:81] op_sel_hi:[1,0]
	v_pk_fma_f32 v[6:7], v[6:7], v[96:97], v[42:43] op_sel:[0,0,0] op_sel_hi:[1,0,1]
	v_pk_mul_f32 v[38:39], v[6:7], v[80:81] op_sel:[0,1] op_sel_hi:[1,1]
	v_pk_mul_f32 v[44:45], v[104:105], v[82:83] op_sel_hi:[1,0]
	v_pk_fma_f32 v[8:9], v[8:9], v[96:97], v[44:45] op_sel:[0,1,0] op_sel_hi:[1,1,1]
	v_pk_fma_f32 v[38:39], v[8:9], v[82:83], v[38:39] op_sel:[0,1,0] op_sel_hi:[1,1,1]
	v_pk_mul_f32 v[42:43], v[104:105], v[84:85] op_sel_hi:[1,0]
	v_pk_fma_f32 v[10:11], v[10:11], v[98:99], v[42:43] op_sel:[0,0,0] op_sel_hi:[1,0,1]
	v_pk_fma_f32 v[38:39], v[10:11], v[84:85], v[38:39] op_sel:[0,1,0] op_sel_hi:[1,1,1]
	v_pk_mul_f32 v[44:45], v[104:105], v[86:87] op_sel_hi:[1,0]
	v_pk_fma_f32 v[12:13], v[12:13], v[98:99], v[44:45] op_sel:[0,1,0] op_sel_hi:[1,1,1]
	v_pk_fma_f32 v[38:39], v[12:13], v[86:87], v[38:39] op_sel:[0,1,0] op_sel_hi:[1,1,1]
	v_pk_mul_f32 v[42:43], v[104:105], v[88:89] op_sel_hi:[1,0]
	v_pk_fma_f32 v[14:15], v[14:15], v[100:101], v[42:43] op_sel:[0,0,0] op_sel_hi:[1,0,1]
	v_pk_fma_f32 v[38:39], v[14:15], v[88:89], v[38:39] op_sel:[0,1,0] op_sel_hi:[1,1,1]
	v_pk_mul_f32 v[44:45], v[104:105], v[90:91] op_sel_hi:[1,0]
	v_pk_fma_f32 v[16:17], v[16:17], v[100:101], v[44:45] op_sel:[0,1,0] op_sel_hi:[1,1,1]
	v_pk_fma_f32 v[38:39], v[16:17], v[90:91], v[38:39] op_sel:[0,1,0] op_sel_hi:[1,1,1]
	v_pk_mul_f32 v[42:43], v[104:105], v[92:93] op_sel_hi:[1,0]
	v_pk_fma_f32 v[18:19], v[18:19], v[102:103], v[42:43] op_sel:[0,0,0] op_sel_hi:[1,0,1]
	v_pk_fma_f32 v[38:39], v[18:19], v[92:93], v[38:39] op_sel:[0,1,0] op_sel_hi:[1,1,1]
	v_pk_mul_f32 v[44:45], v[104:105], v[94:95] op_sel_hi:[1,0]
	v_pk_fma_f32 v[20:21], v[20:21], v[102:103], v[44:45] op_sel:[0,1,0] op_sel_hi:[1,1,1]
	v_pk_fma_f32 v[38:39], v[20:21], v[94:95], v[38:39] op_sel:[0,1,0] op_sel_hi:[1,1,1]
	s_add_u32 s14, s14, 0x1000
	s_addc_u32 s15, s15, 0
	v_add_f32_dpp v38, v38, v38 row_ror:8 row_mask:0xf bank_mask:0x3 bound_ctrl:1
	v_add_f32_dpp v38, v39, v39 row_ror:8 row_mask:0xf bank_mask:0xc bound_ctrl:1
	ds_read_b128 v[48:51], v24 offset:0
	ds_read_b128 v[52:55], v24 offset:256
	v_add_f32_dpp v38, v38, v38 row_half_mirror row_mask:0xf bank_mask:0xf bound_ctrl:1
	ds_read_b128 v[56:59], v24 offset:512
	ds_read_b128 v[60:63], v24 offset:768
	v_add_f32_dpp v38, v38, v38 quad_perm:[1,0,3,2] row_mask:0xf bank_mask:0xf bound_ctrl:1
	ds_read_b128 v[64:67], v24 offset:16384
	ds_read_b128 v[68:71], v24 offset:16640
	v_add_f32_dpp v38, v38, v38 quad_perm:[2,3,0,1] row_mask:0xf bank_mask:0xf bound_ctrl:1
	ds_read_b64 v[72:73], v25 offset:20480
	s_nop 0
	v_mov_b32_dpp v39, v38 row_ror:8 row_mask:0xf bank_mask:0xf bound_ctrl:1
	v_pk_mul_f32 v[38:39], v[38:39], v[40:41] op_sel_hi:[1,0]
	v_cvt_pk_bf16_f32 v47, v38, v39
	s_mov_b64 exec, s[2:3]
	global_store_dword v46, v47, s[14:15] offset:-4096
	s_mov_b64 exec, -1
	s_waitcnt vmcnt(8)
	v_lshlrev_b32_e32 v144, 16, v110
	v_lshlrev_b32_e32 v145, 16, v111
	v_and_b32_e32 v146, s17, v110
	v_and_b32_e32 v147, s17, v111
	v_lshlrev_b32_e32 v148, 16, v112
	v_lshlrev_b32_e32 v149, 16, v113
	v_and_b32_e32 v150, s17, v112
	v_and_b32_e32 v151, s17, v113
	v_lshlrev_b32_e32 v152, 16, v114
	v_and_b32_e32 v153, s17, v114
	ds_write_b128 v26, v[144:147] offset:0
	ds_write_b128 v26, v[148:151] offset:8192
	ds_write_b64 v27, v[116:117]
	ds_write_b64 v28, v[152:153]
	s_mov_b32 s0, s20
	s_mov_b32 s20, s21
	s_mov_b32 s21, s22
	s_mov_b32 s22, s0
	v_mov_b32_e32 v22, v24
	v_mov_b32_e32 v23, v25
	v_add_u32_e32 v24, s21, v2
	v_add_u32_e32 v25, s21, v3
	v_add_u32_e32 v26, s22, v29
	v_add_u32_e32 v27, s22, v30
	v_add_u32_e32 v28, s22, v31
	s_waitcnt lgkmcnt(0)
	s_barrier
	s_add_i32 s16, s16, 8
	s_cmpk_lt_u32 s16, 0x800
	s_cbranch_scc1 .Lgla2_loop
	v_readlane_b32 s0, v255, 18
	v_readlane_b32 s1, v255, 19
	s_load_dwordx2 s[2:3], s[0:1], 0xe8
	s_lshr_b32 s0, s18, 5
	s_lshl_b32 s4, s0, 17
	s_add_u32 s4, s4, 74236160
	v_lshl_add_u32 v42, v46, 1, v4
	s_waitcnt lgkmcnt(0)
	s_add_u32 s2, s2, s4
	s_addc_u32 s3, s3, 0
	global_store_dwordx2 v42, v[6:7], s[2:3] offset:0
	global_store_dwordx2 v42, v[8:9], s[2:3] offset:1024
	global_store_dwordx2 v42, v[10:11], s[2:3] offset:2048
	global_store_dwordx2 v42, v[12:13], s[2:3] offset:3072
	s_add_u32 s2, s2, 0x1000
	s_addc_u32 s3, s3, 0
	global_store_dwordx2 v42, v[14:15], s[2:3] offset:0
	global_store_dwordx2 v42, v[16:17], s[2:3] offset:1024
	global_store_dwordx2 v42, v[18:19], s[2:3] offset:2048
	global_store_dwordx2 v42, v[20:21], s[2:3] offset:3072
	s_add_i32 s18, s18, s19
	s_waitcnt vmcnt(0)
	s_cmpk_lt_i32 s18, 0x400
	s_cbranch_scc1 .Lgla2_item
	s_branch .LBB0_80
